# attention: end-of-round barrier moved to the next round top after the Q/K loads are issued; V staging and bias load after it; bias LDS write deferred
# speedup vs baseline: 1.0034x; 1.0034x over previous
; __device__ __forceinline__ void attn_phase(LAS unsigned char* lds, bf16_t* qkv, float* lse, const float* biasT, int G) {
;     ...
;     { const int pair0 = attn_pair(0, cwg, G); if (pair0 < 4608) { const AttnItem a = attn_item(pair0 * 2 + half); attn_load_v(a, qkv, ht, vreg); } }
;     __syncthreads();
;     for (int j = 0; j < nrounds; ++j) {
.Lattn_stag_in:
	s_waitcnt vmcnt(0)
	s_branch .LBB0_414

; #define LAS __attribute__((address_space(3)))
; #define ATT_LOADK(buf, grp) do { _Pragma("unroll") for (int tt = 0; tt < 3; ++tt) { int ki = kbase + 16 * ((grp) * 3 + tt); ki = ki < 0 ? 0 : (ki > a.m - 1 ? a.m - 1 : ki); \
;             const bf16_t* kp = kcol + (size_t)ki * 128; \
;             _Pragma("unroll") for (int ks = 0; ks < 4; ++ks) Kf[buf][tt][ks] = *(const bf16x8*)(kp + 32 * ks); } } while (0)
; __device__ __forceinline__ void attn_phase(LAS unsigned char* lds, bf16_t* qkv, float* lse, const float* biasT, int G) {
;     ...
;         const int pair = attn_pair(j, cwg, G); if (pair >= 4608) break;
;         const int pairn = (j + 1 < nrounds) ? attn_pair(j + 1, cwg, G) : 4608;
;         const AttnItem a = attn_item(pair * 2 + half);
; #pragma unroll
;         for (int pass = 0; pass < 12; ++pass) *(LAS u32x4*)(vs + (pass * 16 + (ht >> 4)) * VS_PITCH + (ht & 15) * 16) = vreg[pass];
;         if (ht < 129) bs[16 + ht] = biasT[a.head * 132 + ht];
;         __syncthreads();
;         const size_t tokq = (size_t)(a.pos0 + a.r + ((16 * w4 + li) << a.dsh));
;         const int pbase = a.seq_base + a.r * a.m;
;         bf16_t* qp = qkv + ((size_t)a.head * M_TOK + pbase + a.i0 + 16 * w4 + li) * 128;
;         bf16x8 Qf[4];
; #pragma unroll
;         for (int ks = 0; ks < 4; ++ks) Qf[ks] = *(const bf16x8*)(qp + 32 * ks + 8 * lg);
;         const int kbase = a.i0 - 64 + 16 * w4 + li;
;         const bf16_t* kcol = qkv + ((size_t)(12 + a.head) * M_TOK + pbase) * 128 + 8 * lg;
;         f32x4 sa[10];
;         bf16x8 Kf[2][3][4];
;     ...
;         ATT_LOADK(0, 0); ATT_LOADK(1, 1);
.LBB0_423:
	s_lshl_b32 s9, s11, 1
	s_add_i32 s9, s9, s94
	s_mul_hi_i32 s0, s9, 0x2aaaaaab
	s_lshr_b32 s1, s0, 31
	s_ashr_i32 s0, s0, 7
	s_add_i32 s10, s0, s1
	s_mul_i32 s0, s10, 0xfffffd00
	s_add_i32 s0, s0, s9
	s_lshl_b32 s1, s0, 6
	s_and_b32 s9, s1, 0xffffe000
	s_cmpk_lt_i32 s0, 0x200
	s_cselect_b32 s0, 13, 14
	s_cselect_b32 s9, s9, 0x8000
	s_ashr_i32 s11, s10, 1
	s_and_b32 s12, s11, -2
	s_sub_i32 s11, s0, s12
	s_sub_i32 s30, s1, s9
	s_ashr_i32 s96, s30, s11
	s_lshl_b32 s31, s96, s11
	s_sub_i32 s13, s30, s31
	s_add_i32 s16, s31, s9
	s_mul_hi_i32 s0, s10, 0xc000
	s_ashr_i32 s18, s16, 31
	s_ashr_i32 s1, s13, 31
	s_mul_i32 s17, s10, 0xc000
	v_mov_b32_e32 v3, s0
	s_add_u32 s0, s13, s16
	v_or_b32_e32 v2, s17, v184
	s_addc_u32 s1, s1, s18
	v_lshl_add_u64 v[2:3], s[0:1], 0, v[2:3]
	v_readlane_b32 s0, v250, 21
	s_add_i32 s15, s13, s0
	s_add_i32 s0, s10, 12
	s_add_i32 s17, s17, 0x90000
	v_lshlrev_b64 v[2:3], 8, v[2:3]
	s_mul_hi_i32 s1, s0, 0xc000
	s_add_u32 s0, s17, s16
	v_lshl_add_u64 v[194:195], s[92:93], 0, v[2:3]
	v_mov_b32_e32 v191, v1
	s_addc_u32 s1, s1, s18
	v_lshl_add_u64 v[2:3], v[194:195], 0, v[190:191]
	s_lshl_b64 s[0:1], s[0:1], 8
	global_load_dwordx4 v[96:99], v[2:3], off
	global_load_dwordx4 v[92:95], v[2:3], off offset:64
	global_load_dwordx4 v[88:91], v[2:3], off offset:128
	global_load_dwordx4 v[52:55], v[2:3], off offset:192
	v_add_u32_e32 v0, s15, v216
	v_lshl_add_u64 v[2:3], v[186:187], 0, s[0:1]
	s_bfm_b32 s0, s11, 0
	v_min_i32_e32 v56, s0, v0
	v_ashrrev_i32_e32 v57, 31, v56
	v_lshlrev_b64 v[56:57], 7, v[56:57]
	v_cmp_lt_i32_e32 vcc, -1, v0
	s_movk_i32 s1, 0xffef
	v_add_u32_e32 v58, 48, v0
	v_cndmask_b32_e32 v57, 0, v57, vcc
	v_cndmask_b32_e32 v56, 0, v56, vcc
	v_lshl_add_u64 v[56:57], v[56:57], 1, v[2:3]
	global_load_dwordx4 v[68:71], v[56:57], off
	global_load_dwordx4 v[72:75], v[56:57], off offset:64
	global_load_dwordx4 v[80:83], v[56:57], off offset:128
	global_load_dwordx4 v[84:87], v[56:57], off offset:192
	v_add_u32_e32 v56, 16, v0
	v_min_i32_e32 v56, s0, v56
	v_ashrrev_i32_e32 v57, 31, v56
	v_lshlrev_b64 v[56:57], 7, v[56:57]
	v_cmp_lt_i32_e32 vcc, s1, v0
	s_movk_i32 s1, 0xffdf
	v_add_u32_e32 v102, 64, v0
	v_cndmask_b32_e32 v57, 0, v57, vcc
	v_cndmask_b32_e32 v56, 0, v56, vcc
	v_lshl_add_u64 v[56:57], v[56:57], 1, v[2:3]
	global_load_dwordx4 v[116:119], v[56:57], off
	global_load_dwordx4 v[136:139], v[56:57], off offset:64
	global_load_dwordx4 v[140:143], v[56:57], off offset:128
	global_load_dwordx4 v[144:147], v[56:57], off offset:192
	v_add_u32_e32 v56, 32, v0
	v_min_i32_e32 v56, s0, v56
	v_ashrrev_i32_e32 v57, 31, v56
	v_lshlrev_b64 v[56:57], 7, v[56:57]
	v_cmp_lt_i32_e32 vcc, s1, v0
	v_min_i32_e32 v100, s0, v102
	v_add_u32_e32 v122, 0x50, v0
	v_cndmask_b32_e32 v57, 0, v57, vcc
	v_cndmask_b32_e32 v56, 0, v56, vcc
	v_lshl_add_u64 v[56:57], v[56:57], 1, v[2:3]
	global_load_dwordx4 v[148:151], v[56:57], off
	global_load_dwordx4 v[152:155], v[56:57], off offset:64
	global_load_dwordx4 v[156:159], v[56:57], off offset:128
	global_load_dwordx4 v[160:163], v[56:57], off offset:192
	v_min_i32_e32 v56, s0, v58
	v_ashrrev_i32_e32 v57, 31, v56
	v_lshlrev_b64 v[56:57], 7, v[56:57]
	v_cmp_lt_i32_e32 vcc, -1, v58
	v_ashrrev_i32_e32 v101, 31, v100
	v_min_i32_e32 v120, s0, v122
	v_cndmask_b32_e32 v57, 0, v57, vcc
	v_cndmask_b32_e32 v56, 0, v56, vcc
	v_lshlrev_b64 v[100:101], 7, v[100:101]
	v_cmp_lt_i32_e32 vcc, -1, v102
	v_ashrrev_i32_e32 v121, 31, v120
	v_lshlrev_b64 v[120:121], 7, v[120:121]
	v_cndmask_b32_e32 v101, 0, v101, vcc
	v_cndmask_b32_e32 v100, 0, v100, vcc
	v_cmp_lt_i32_e32 vcc, -1, v122
	v_lshl_add_u64 v[76:77], v[56:57], 1, v[2:3]
	v_lshl_add_u64 v[112:113], v[100:101], 1, v[2:3]
	v_cndmask_b32_e32 v121, 0, v121, vcc
	v_cndmask_b32_e32 v120, 0, v120, vcc
	v_lshl_add_u64 v[132:133], v[120:121], 1, v[2:3]
	global_load_dwordx4 v[56:59], v[76:77], off
	global_load_dwordx4 v[60:63], v[76:77], off offset:64
	global_load_dwordx4 v[64:67], v[76:77], off offset:128
	s_nop 0
	global_load_dwordx4 v[76:79], v[76:77], off offset:192
	s_nop 0
	global_load_dwordx4 v[100:103], v[112:113], off
	global_load_dwordx4 v[104:107], v[112:113], off offset:64
	global_load_dwordx4 v[108:111], v[112:113], off offset:128
	s_nop 0
	global_load_dwordx4 v[112:115], v[112:113], off offset:192
	s_nop 0
	global_load_dwordx4 v[120:123], v[132:133], off
	global_load_dwordx4 v[124:127], v[132:133], off offset:64
	global_load_dwordx4 v[128:131], v[132:133], off offset:128
	s_nop 0
	global_load_dwordx4 v[132:135], v[132:133], off offset:192
	s_barrier
; #define LAS __attribute__((address_space(3)))
; #define ATT_LOADK(buf, grp) do { _Pragma("unroll") for (int tt = 0; tt < 3; ++tt) { int ki = kbase + 16 * ((grp) * 3 + tt); ki = ki < 0 ? 0 : (ki > a.m - 1 ? a.m - 1 : ki); \
;             const bf16_t* kp = kcol + (size_t)ki * 128; \
;             _Pragma("unroll") for (int ks = 0; ks < 4; ++ks) Kf[buf][tt][ks] = *(const bf16x8*)(kp + 32 * ks); } } while (0)
; #define ATT_MMAK(buf, grp) do { _Pragma("unroll") for (int tt = 0; tt < 3; ++tt) { f32x4 acc_ = (f32x4){0.f, 0.f, 0.f, 0.f}; \
;             _Pragma("unroll") for (int ks = 0; ks < 4; ++ks) acc_ = __builtin_amdgcn_mfma_f32_16x16x32_bf16(Kf[buf][tt][ks], Qf[ks], acc_, 0, 0, 0); sa[(grp) * 3 + tt] = acc_; } } while (0)
; __device__ __forceinline__ void attn_phase(LAS unsigned char* lds, bf16_t* qkv, float* lse, const float* biasT, int G) {
;     ...
;         for (int pass = 0; pass < 12; ++pass) *(LAS u32x4*)(vs + (pass * 16 + (ht >> 4)) * VS_PITCH + (ht & 15) * 16) = vreg[pass];
;         if (ht < 129) bs[16 + ht] = biasT[a.head * 132 + ht];
;     ...
;         ATT_LOADK(0, 0); ATT_LOADK(1, 1);
;         __builtin_amdgcn_sched_barrier(0);
;         ATT_MMAK(0, 0);
;         __builtin_amdgcn_sched_barrier(0);
;         ATT_LOADK(0, 2);
;         if (pairn < 4608) { const AttnItem an = attn_item(pairn * 2 + half); attn_load_v(an, qkv, ht, vreg); }
	ds_write_b128 v231, v[8:11]
	ds_write_b128 v231, v[4:7] offset:4608
	ds_write_b128 v231, v[12:15] offset:9216
	ds_write_b128 v231, v[16:19] offset:13824
	ds_write_b128 v231, v[20:23] offset:18432
	ds_write_b128 v231, v[24:27] offset:23040
	ds_write_b128 v231, v[28:31] offset:27648
	ds_write_b128 v231, v[32:35] offset:32256
	ds_write_b128 v231, v[36:39] offset:36864
	ds_write_b128 v231, v[40:43] offset:41472
	ds_write_b128 v231, v[44:47] offset:46080
	ds_write_b128 v231, v[48:51] offset:50688
	s_mul_i32 s32, s10, 0x84
	v_add_u32_e32 v254, s32, v183
	v_ashrrev_i32_e32 v255, 31, v254
	v_readlane_b32 vcc_lo, v250, 13
	v_readlane_b32 vcc_hi, v250, 14
	s_nop 1
	v_lshl_add_u64 v[254:255], v[254:255], 2, vcc
	v_readlane_b32 s32, v250, 1
	s_mov_b32 exec_lo, s32
	v_readlane_b32 s32, v250, 2
	s_mov_b32 exec_hi, s32
	s_nop 0
	global_load_dword v253, v[254:255], off
	s_mov_b64 exec, -1
	s_waitcnt vmcnt(23)
	v_mfma_f32_16x16x32_bf16 v[68:71], v[68:71], v[96:99], 0
	s_waitcnt vmcnt(22)
	v_mfma_f32_16x16x32_bf16 v[68:71], v[72:75], v[92:95], v[68:71]
	s_waitcnt vmcnt(21)
	v_mfma_f32_16x16x32_bf16 v[68:71], v[80:83], v[88:91], v[68:71]
	s_waitcnt vmcnt(20)
	v_mfma_f32_16x16x32_bf16 v[84:87], v[84:87], v[52:55], v[68:71]
	s_waitcnt vmcnt(19)
	v_mfma_f32_16x16x32_bf16 v[68:71], v[116:119], v[96:99], 0
	s_waitcnt vmcnt(18)
	v_mfma_f32_16x16x32_bf16 v[68:71], v[136:139], v[92:95], v[68:71]
	s_waitcnt vmcnt(17)
	v_mfma_f32_16x16x32_bf16 v[68:71], v[140:143], v[88:91], v[68:71]
	s_waitcnt vmcnt(16)
	v_mfma_f32_16x16x32_bf16 v[72:75], v[144:147], v[52:55], v[68:71]
	s_waitcnt vmcnt(15)
	v_mfma_f32_16x16x32_bf16 v[68:71], v[148:151], v[96:99], 0
	s_waitcnt vmcnt(14)
	v_mfma_f32_16x16x32_bf16 v[68:71], v[152:155], v[92:95], v[68:71]
	s_waitcnt vmcnt(13)
	v_mfma_f32_16x16x32_bf16 v[68:71], v[156:159], v[88:91], v[68:71]
	s_waitcnt vmcnt(12)
	v_mfma_f32_16x16x32_bf16 v[68:71], v[160:163], v[52:55], v[68:71]
	v_add_u32_e32 v82, 0x60, v0
	v_min_i32_e32 v80, s0, v82
	v_ashrrev_i32_e32 v81, 31, v80
	v_lshlrev_b64 v[80:81], 7, v[80:81]
	v_cmp_lt_i32_e32 vcc, -1, v82
	v_add_u32_e32 v82, 0x70, v0
	v_add_u32_e32 v0, 0x80, v0
	v_cndmask_b32_e32 v81, 0, v81, vcc
	v_cndmask_b32_e32 v80, 0, v80, vcc
	v_lshl_add_u64 v[80:81], v[80:81], 1, v[2:3]
	global_load_dwordx4 v[136:139], v[80:81], off
	global_load_dwordx4 v[140:143], v[80:81], off offset:64
	global_load_dwordx4 v[144:147], v[80:81], off offset:128
	global_load_dwordx4 v[148:151], v[80:81], off offset:192
	v_min_i32_e32 v80, s0, v82
	v_ashrrev_i32_e32 v81, 31, v80
	v_lshlrev_b64 v[80:81], 7, v[80:81]
	v_cmp_lt_i32_e32 vcc, -1, v82
	s_cmpk_gt_i32 s14, 0x11ff
	s_nop 0
	v_cndmask_b32_e32 v81, 0, v81, vcc
	v_cndmask_b32_e32 v80, 0, v80, vcc
	v_lshl_add_u64 v[80:81], v[80:81], 1, v[2:3]
	global_load_dwordx4 v[152:155], v[80:81], off
	global_load_dwordx4 v[156:159], v[80:81], off offset:64
	global_load_dwordx4 v[160:163], v[80:81], off offset:128
	global_load_dwordx4 v[164:167], v[80:81], off offset:192
	v_min_i32_e32 v80, s0, v0
	v_ashrrev_i32_e32 v81, 31, v80
	v_lshlrev_b64 v[80:81], 7, v[80:81]
	v_cmp_lt_i32_e32 vcc, -1, v0
	s_nop 1
	v_cndmask_b32_e32 v81, 0, v81, vcc
	v_cndmask_b32_e32 v80, 0, v80, vcc
	v_lshl_add_u64 v[2:3], v[80:81], 1, v[2:3]
	global_load_dwordx4 v[176:179], v[2:3], off
	global_load_dwordx4 v[172:175], v[2:3], off offset:64
	global_load_dwordx4 v[168:171], v[2:3], off offset:128
	global_load_dwordx4 v[116:119], v[2:3], off offset:192
	s_cbranch_scc1 .LBB0_451
	s_lshl_b32 s0, s14, 1
	s_add_i32 s0, s0, s94
	s_mul_hi_i32 s1, s0, 0x2aaaaaab
	s_lshr_b32 s14, s1, 31
	s_ashr_i32 s1, s1, 7
	s_add_i32 s14, s1, s14
	s_mul_i32 s1, s14, 0xfffffd00
	s_add_i32 s1, s1, s0
	s_lshl_b32 s0, s1, 6
	s_and_b32 s16, s0, 0xffffe000
	s_cmpk_lt_i32 s1, 0x200
	s_cselect_b32 s1, 13, 14
	s_cselect_b32 s16, s16, 0x8000
	s_ashr_i32 s17, s14, 1
	s_and_b32 s17, s17, -2
	s_sub_i32 s1, s1, s17
	s_lshl_b32 s18, 1, s1
	s_sub_i32 s0, s0, s16
	s_lshl_b32 s1, -1, s1
	s_and_b32 s17, s1, s0
	s_sub_i32 s19, s0, s17
	s_cmp_lt_i32 s19, 64
	s_cbranch_scc1 .Lattn_vslow
	s_add_i32 s0, s19, 0x80
	s_cmp_gt_i32 s0, s18
	s_cbranch_scc1 .Lattn_vslow
	s_add_i32 s28, s14, 24
	s_mul_i32 s28, s28, 0xc000
	s_add_i32 s28, s28, s16
	s_add_i32 s28, s28, s17
	s_add_i32 s28, s28, s19
	v_add_u32_e32 v0, s28, v220
	v_lshlrev_b32_e32 v0, 8, v0
	s_mov_b64 s[28:29], 0x1000
	v_lshl_add_u64 v[2:3], v[188:189], 0, v[0:1]
	v_lshl_add_u64 v[2:3], s[28:29], 0, v[2:3]
	s_mov_b64 s[28:29], 0x2000
	global_load_dwordx4 v[8:11], v[2:3], off offset:-4096
	global_load_dwordx4 v[4:7], v[2:3], off
	v_lshl_add_u64 v[2:3], s[28:29], 0, v[2:3]
	global_load_dwordx4 v[12:15], v[2:3], off offset:-4096
	global_load_dwordx4 v[16:19], v[2:3], off
	v_lshl_add_u64 v[2:3], s[28:29], 0, v[2:3]
	global_load_dwordx4 v[20:23], v[2:3], off offset:-4096
	global_load_dwordx4 v[24:27], v[2:3], off
	v_lshl_add_u64 v[2:3], s[28:29], 0, v[2:3]
	global_load_dwordx4 v[28:31], v[2:3], off offset:-4096
	global_load_dwordx4 v[32:35], v[2:3], off
	v_lshl_add_u64 v[2:3], s[28:29], 0, v[2:3]
	global_load_dwordx4 v[36:39], v[2:3], off offset:-4096
	global_load_dwordx4 v[40:43], v[2:3], off
	v_lshl_add_u64 v[2:3], s[28:29], 0, v[2:3]
	global_load_dwordx4 v[44:47], v[2:3], off offset:-4096
	global_load_dwordx4 v[48:51], v[2:3], off
	s_branch .LBB0_451

; #define ATT_LOADK(buf, grp) do { _Pragma("unroll") for (int tt = 0; tt < 3; ++tt) { int ki = kbase + 16 * ((grp) * 3 + tt); ki = ki < 0 ? 0 : (ki > a.m - 1 ? a.m - 1 : ki); \
;             const bf16_t* kp = kcol + (size_t)ki * 128; \
;             _Pragma("unroll") for (int ks = 0; ks < 4; ++ks) Kf[buf][tt][ks] = *(const bf16x8*)(kp + 32 * ks); } } while (0)
; #define ATT_MMAK(buf, grp) do { _Pragma("unroll") for (int tt = 0; tt < 3; ++tt) { f32x4 acc_ = (f32x4){0.f, 0.f, 0.f, 0.f}; \
;             _Pragma("unroll") for (int ks = 0; ks < 4; ++ks) acc_ = __builtin_amdgcn_mfma_f32_16x16x32_bf16(Kf[buf][tt][ks], Qf[ks], acc_, 0, 0, 0); sa[(grp) * 3 + tt] = acc_; } } while (0)
; __device__ __forceinline__ void attn_phase(LAS unsigned char* lds, bf16_t* qkv, float* lse, const float* biasT, int G) {
;     ...
;         if (ht < 129) bs[16 + ht] = biasT[a.head * 132 + ht];
;     ...
;         ATT_LOADK(0, 0); ATT_LOADK(1, 1);
;         __builtin_amdgcn_sched_barrier(0);
;         ATT_MMAK(0, 0);
;         __builtin_amdgcn_sched_barrier(0);
;         ATT_LOADK(0, 2);
;         if (pairn < 4608) { const AttnItem an = attn_item(pairn * 2 + half); attn_load_v(an, qkv, ht, vreg); }
;         __builtin_amdgcn_sched_barrier(0);
;         ATT_MMAK(1, 1);
;         ATT_MMAK(0, 2);
;     ...
;         sa[9] = (f32x4){0.f, 0.f, 0.f, 0.f};
;         const int kabs0 = a.i0 - 64 + 16 * w4 + 4 * lg;
;         const bool edge = (a.i0 == 0) || (a.i0 + 64 == a.m);
;         float mx = edge ? attn_scores<true>(sa, bsl, dl, kabs0, a.m, scale2) : attn_scores<false>(sa, bsl, dl, kabs0, a.m, scale2);
.LBB0_451:
	s_lshl_b32 s14, 1, s11
	s_ashr_i32 s11, s10, 31
	s_waitcnt vmcnt(23)
	v_mfma_f32_16x16x32_bf16 v[56:59], v[56:59], v[96:99], 0
	s_cmp_eq_u32 s30, s31
	s_cselect_b64 s[0:1], -1, 0
	s_add_i32 s16, s13, 64
	s_waitcnt vmcnt(22)
	v_mfma_f32_16x16x32_bf16 v[56:59], v[60:63], v[92:95], v[56:59]
	s_cmp_eq_u32 s16, s14
	s_cselect_b64 s[16:17], -1, 0
	s_or_b64 s[16:17], s[0:1], s[16:17]
	s_waitcnt vmcnt(21)
	v_mfma_f32_16x16x32_bf16 v[56:59], v[64:67], v[88:91], v[56:59]
	s_mov_b64 s[0:1], -1
	s_andn2_b64 vcc, exec, s[16:17]
	s_waitcnt vmcnt(20)
	v_mfma_f32_16x16x32_bf16 v[80:83], v[76:79], v[52:55], v[56:59]
	s_waitcnt vmcnt(19)
	v_mfma_f32_16x16x32_bf16 v[56:59], v[100:103], v[96:99], 0
	s_waitcnt vmcnt(18)
	v_mfma_f32_16x16x32_bf16 v[56:59], v[104:107], v[92:95], v[56:59]
	s_waitcnt vmcnt(17)
	v_mfma_f32_16x16x32_bf16 v[56:59], v[108:111], v[88:91], v[56:59]
	s_waitcnt vmcnt(16)
	v_mfma_f32_16x16x32_bf16 v[76:79], v[112:115], v[52:55], v[56:59]
	s_waitcnt vmcnt(15)
	v_mfma_f32_16x16x32_bf16 v[56:59], v[120:123], v[96:99], 0
	s_waitcnt vmcnt(14)
	v_mfma_f32_16x16x32_bf16 v[56:59], v[124:127], v[92:95], v[56:59]
	s_waitcnt vmcnt(13)
	v_mfma_f32_16x16x32_bf16 v[56:59], v[128:131], v[88:91], v[56:59]
	s_waitcnt vmcnt(12)
	v_mfma_f32_16x16x32_bf16 v[64:67], v[132:135], v[52:55], v[56:59]
	s_waitcnt vmcnt(11)
	v_mfma_f32_16x16x32_bf16 v[56:59], v[136:139], v[96:99], 0
	s_waitcnt vmcnt(10)
	v_mfma_f32_16x16x32_bf16 v[56:59], v[140:143], v[92:95], v[56:59]
	s_waitcnt vmcnt(9)
	v_mfma_f32_16x16x32_bf16 v[56:59], v[144:147], v[88:91], v[56:59]
	s_waitcnt vmcnt(8)
	v_mfma_f32_16x16x32_bf16 v[60:63], v[148:151], v[52:55], v[56:59]
	s_waitcnt vmcnt(7)
	v_mfma_f32_16x16x32_bf16 v[56:59], v[152:155], v[96:99], 0
	s_waitcnt vmcnt(3)
	v_mfma_f32_16x16x32_bf16 v[96:99], v[176:179], v[96:99], 0
	v_mfma_f32_16x16x32_bf16 v[56:59], v[156:159], v[92:95], v[56:59]
	s_waitcnt vmcnt(2)
	v_mfma_f32_16x16x32_bf16 v[92:95], v[172:175], v[92:95], v[96:99]
	v_mfma_f32_16x16x32_bf16 v[56:59], v[160:163], v[88:91], v[56:59]
	s_waitcnt vmcnt(1)
	v_mfma_f32_16x16x32_bf16 v[126:129], v[168:171], v[88:91], v[92:95]
	v_mfma_f32_16x16x32_bf16 v[56:59], v[164:167], v[52:55], v[56:59]
	s_waitcnt vmcnt(0)
	v_mfma_f32_16x16x32_bf16 v[52:55], v[116:119], v[52:55], v[126:129]
	v_readlane_b32 s32, v250, 1
	s_mov_b32 exec_lo, s32
	v_readlane_b32 s32, v250, 2
	s_mov_b32 exec_hi, s32
	s_nop 0
	ds_write_b32 v185, v253 offset:64
	s_mov_b64 exec, -1
	s_waitcnt lgkmcnt(0)
	s_barrier
	s_cbranch_vccz .LBB0_453
	ds_read2_b32 v[2:3], v218 offset0:16 offset1:17
	s_mov_b32 s0, 0x3e0293ee
	v_readlane_b32 s16, v250, 22
	v_readlane_b32 s17, v250, 23
	s_waitcnt lgkmcnt(0)
	v_pk_fma_f32 v[2:3], v[84:85], s[0:1], v[2:3] op_sel_hi:[1,0,1]
	s_nop 0
	v_cndmask_b32_e64 v0, v212, v3, s[16:17]
	v_readlane_b32 s16, v250, 17
	v_readlane_b32 s17, v250, 18
	s_nop 1
	v_cndmask_b32_e64 v114, v212, v2, s[16:17]
	ds_read2_b32 v[2:3], v218 offset0:18 offset1:19
	v_readlane_b32 s16, v250, 24
	v_readlane_b32 s17, v250, 25
	v_max_f32_e32 v88, 0xff61b1e6, v114
	s_waitcnt lgkmcnt(0)
	v_pk_fma_f32 v[2:3], v[86:87], s[0:1], v[2:3] op_sel_hi:[1,0,1]
	s_nop 0
	v_cndmask_b32_e64 v120, v212, v3, s[16:17]
	v_readlane_b32 s16, v251, 63
	v_readlane_b32 s17, v250, 0
	s_nop 1
	v_cndmask_b32_e64 v115, v212, v2, s[16:17]
	ds_read2_b32 v[2:3], v218 offset0:32 offset1:33
	v_max3_f32 v88, v88, v0, v115
	s_waitcnt lgkmcnt(0)
	v_pk_fma_f32 v[2:3], v[72:73], s[0:1], v[2:3] op_sel_hi:[1,0,1]
	s_nop 0
	v_max3_f32 v90, v88, v120, v2
	ds_read2_b32 v[88:89], v218 offset0:34 offset1:35
	s_waitcnt lgkmcnt(0)
	v_pk_fma_f32 v[88:89], v[74:75], s[0:1], v[88:89] op_sel_hi:[1,0,1]
	s_nop 0
	v_max3_f32 v92, v90, v3, v88
	ds_read2_b32 v[90:91], v218 offset0:48 offset1:49
	s_waitcnt lgkmcnt(0)
	v_pk_fma_f32 v[90:91], v[68:69], s[0:1], v[90:91] op_sel_hi:[1,0,1]
	s_nop 0
	v_max3_f32 v94, v92, v89, v90
	ds_read2_b32 v[92:93], v218 offset0:50 offset1:51
	s_waitcnt lgkmcnt(0)
	v_pk_fma_f32 v[92:93], v[70:71], s[0:1], v[92:93] op_sel_hi:[1,0,1]
	s_nop 0
	v_max3_f32 v96, v94, v91, v92
	ds_read2_b32 v[94:95], v218 offset0:64 offset1:65
	s_waitcnt lgkmcnt(0)
	v_pk_fma_f32 v[94:95], v[80:81], s[0:1], v[94:95] op_sel_hi:[1,0,1]
	s_nop 0
	v_max3_f32 v98, v96, v93, v94
	ds_read2_b32 v[96:97], v218 offset0:66 offset1:67
	s_waitcnt lgkmcnt(0)
	v_pk_fma_f32 v[96:97], v[82:83], s[0:1], v[96:97] op_sel_hi:[1,0,1]
	s_nop 0
	v_max3_f32 v100, v98, v95, v96
	ds_read2_b32 v[98:99], v218 offset0:80 offset1:81
	s_waitcnt lgkmcnt(0)
	v_pk_fma_f32 v[98:99], v[76:77], s[0:1], v[98:99] op_sel_hi:[1,0,1]
	s_nop 0
	v_max3_f32 v102, v100, v97, v98
	ds_read2_b32 v[100:101], v218 offset0:82 offset1:83
	s_waitcnt lgkmcnt(0)
	v_pk_fma_f32 v[100:101], v[78:79], s[0:1], v[100:101] op_sel_hi:[1,0,1]
	s_nop 0
	v_max3_f32 v104, v102, v99, v100
	ds_read2_b32 v[102:103], v218 offset0:96 offset1:97
	s_waitcnt lgkmcnt(0)
	v_pk_fma_f32 v[102:103], v[64:65], s[0:1], v[102:103] op_sel_hi:[1,0,1]
	s_nop 0
	v_max3_f32 v106, v104, v101, v102
	ds_read2_b32 v[104:105], v218 offset0:98 offset1:99
	s_waitcnt lgkmcnt(0)
	v_pk_fma_f32 v[104:105], v[66:67], s[0:1], v[104:105] op_sel_hi:[1,0,1]
	s_nop 0
	v_max3_f32 v108, v106, v103, v104
	ds_read2_b32 v[106:107], v218 offset0:112 offset1:113
	s_waitcnt lgkmcnt(0)
	v_pk_fma_f32 v[106:107], v[60:61], s[0:1], v[106:107] op_sel_hi:[1,0,1]
	s_nop 0
	v_max3_f32 v110, v108, v105, v106
	ds_read2_b32 v[108:109], v218 offset0:114 offset1:115
	s_waitcnt lgkmcnt(0)
	v_pk_fma_f32 v[108:109], v[62:63], s[0:1], v[108:109] op_sel_hi:[1,0,1]
	s_nop 0
	v_max3_f32 v112, v110, v107, v108
	ds_read2_b32 v[110:111], v218 offset0:128 offset1:129
	s_waitcnt lgkmcnt(0)
	v_pk_fma_f32 v[110:111], v[56:57], s[0:1], v[110:111] op_sel_hi:[1,0,1]
	s_nop 0
	v_max3_f32 v116, v112, v109, v110
	ds_read2_b32 v[112:113], v218 offset0:130 offset1:131
	s_waitcnt lgkmcnt(0)
	v_pk_fma_f32 v[112:113], v[58:59], s[0:1], v[112:113] op_sel_hi:[1,0,1]
	s_nop 0
	v_max3_f32 v118, v116, v111, v112
	ds_read2_b32 v[116:117], v218 offset0:144 offset1:145
	s_waitcnt lgkmcnt(0)
	v_pk_fma_f32 v[116:117], v[52:53], s[0:1], v[116:117] op_sel_hi:[1,0,1]
	v_readlane_b32 s0, v250, 11
	v_readlane_b32 s1, v250, 12
	s_nop 1
	v_cndmask_b32_e64 v121, v212, v117, s[0:1]
	ds_read_b32 v117, v218 offset:584
	v_readlane_b32 s0, v250, 9
	v_readlane_b32 s1, v250, 10
	s_waitcnt lgkmcnt(0)
	v_fmac_f32_e32 v117, 0x3e0293ee, v54
	v_cndmask_b32_e64 v122, v212, v116, s[0:1]
	v_max3_f32 v116, v118, v113, v122
	v_cndmask_b32_e64 v123, v212, v117, s[22:23]
	v_max3_f32 v124, v116, v121, v123
	s_mov_b64 s[0:1], 0

; template <bool COOP>
; __global__ void __launch_bounds__(512, 2) fwd_kernel(Params p) {
;     ...
;     }
; }
.LBB0_641:
	s_nop 0
	s_nop 0
	s_nop 0
	s_nop 0
	s_nop 0
	s_nop 0
	s_nop 0
	s_nop 0
	s_nop 0
	s_nop 0
	s_nop 0
	s_nop 0
	s_nop 0
	s_nop 0
	s_nop 0
	s_nop 0
	s_nop 0
	s_nop 0
	s_nop 0
	s_nop 0
	s_nop 0
	s_nop 0
	s_nop 0
	s_nop 0
	s_nop 0
	s_nop 0
	s_nop 0
	s_nop 0
	s_nop 0
	s_nop 0
	s_nop 0
	s_nop 0
	s_nop 0
	s_nop 0
	s_nop 0
	s_nop 0
	s_nop 0
	s_nop 0
	s_nop 0
	s_nop 0
	s_nop 0
	s_nop 0
	s_nop 0
	s_nop 0
	s_nop 0
	s_nop 0
	s_nop 0
	s_nop 0
	s_nop 0
	s_nop 0
	s_nop 0
	s_nop 0
	s_nop 0
	s_nop 0
	s_nop 0
	s_nop 0
	s_nop 0
	s_nop 0
	s_nop 0
	s_nop 0
	s_nop 0
	s_nop 0
	s_nop 0
	s_nop 0
	s_nop 0
	s_nop 0
	s_nop 0
	s_nop 0
	s_nop 0
	s_nop 0
	s_nop 0
	s_nop 0
	s_nop 0
	s_nop 0
	s_nop 0
	s_nop 0
	s_nop 0
	s_nop 0
	s_nop 0
	s_nop 0
	s_nop 0
	s_nop 0
	s_nop 0
	s_nop 0
	s_nop 0
	s_nop 0
	s_nop 0
	s_nop 0
	s_nop 0
	s_nop 0
	s_nop 0
	s_nop 0
	s_nop 0
	s_nop 0
	s_nop 0
	s_nop 0
	s_nop 0
	s_nop 0
	s_nop 0
	s_nop 0
	s_nop 0
	s_nop 0
	s_nop 0
	s_nop 0
	s_nop 0
	s_nop 0
	s_nop 0
	s_nop 0
	s_nop 0
	s_nop 0
	s_nop 0
	s_nop 0
	s_nop 0
	s_nop 0
	s_nop 0
	s_nop 0
	s_nop 0
	s_nop 0
	s_nop 0
	s_nop 0
	s_nop 0
	s_nop 0
	s_nop 0
	s_nop 0
	s_nop 0
	s_nop 0
	s_nop 0
	s_nop 0
	s_nop 0
	s_nop 0
	s_nop 0
	s_nop 0
	s_nop 0
	s_nop 0
	s_nop 0
	s_nop 0
	s_nop 0
	s_nop 0
	s_nop 0
	s_nop 0
	s_nop 0
	s_nop 0
	s_nop 0
	s_nop 0
	s_nop 0
	s_nop 0
	s_nop 0
	s_nop 0
	s_nop 0
	s_nop 0
	s_nop 0
	s_nop 0
	s_nop 0
	s_nop 0
	s_nop 0
	s_nop 0
	s_nop 0
	s_nop 0
	s_nop 0
	s_nop 0
	s_nop 0
	s_nop 0
	s_nop 0
	s_nop 0
	s_nop 0
	s_nop 0
	s_nop 0
	s_nop 0
	s_nop 0
	s_nop 0
	s_nop 0
	s_nop 0
	s_nop 0
	s_nop 0
	s_nop 0
	s_nop 0
	s_nop 0
	s_nop 0
	s_nop 0
	s_nop 0
	s_nop 0
	s_nop 0
	s_nop 0
	s_nop 0
	s_nop 0
	s_nop 0
	s_nop 0
	s_nop 0
	s_nop 0
	s_nop 0
	s_endpgm
